# speedup vs baseline: 1.0264x; 1.0072x over previous
; #define SBAR() __builtin_amdgcn_sched_barrier(0)
; #define MASKT(P0_, P1_, t) do { const int kb_ = KBASE(t); if (kb_ + KVBLK - 1 > qlo) mask_tile(P0_, P1_, qm - kb_, W); } while (0)
; template <int KB>
; __device__ __forceinline__ void qkt(f32x16& p0, f32x16& p1, const char* K_lds, const float* bias_l, int r32, int hi, const bf16x8* qr) {
;     const f32x4* bl = reinterpret_cast<const f32x4*>(bias_l + KB * 64);
; #pragma unroll
;     for (int g = 0; g < 4; ++g) { const f32x4 b0 = bl[2 * g + hi], b1 = bl[8 + 2 * g + hi];
;         p0[4 * g + 0] = b0[0]; p0[4 * g + 1] = b0[1]; p0[4 * g + 2] = b0[2]; p0[4 * g + 3] = b0[3];
;         p1[4 * g + 0] = b1[0]; p1[4 * g + 1] = b1[1]; p1[4 * g + 2] = b1[2]; p1[4 * g + 3] = b1[3]; }
;     const char* kb[4];
; #pragma unroll
;     for (int dd = 0; dd < 4; ++dd) kb[dd] = K_lds + KB * SHM_K + KSWZ(r32, (dd * 16 + hi * 8) * 2);
; #pragma unroll
;     for (int d0 = 0; d0 < 8; ++d0) { const char* a = kb[d0 & 3] + (d0 >> 2) * 128;
;         bf16x8 b0 = *reinterpret_cast<const bf16x8*>(a);
;         bf16x8 b1 = *reinterpret_cast<const bf16x8*>(a + 32 * 256);
;         p0 = __builtin_amdgcn_mfma_f32_32x32x16_bf16(b0, qr[d0], p0, 0, 0, 0);
;         p1 = __builtin_amdgcn_mfma_f32_32x32x16_bf16(b1, qr[d0], p1, 0, 0, 0); }
; }
; __device__ __forceinline__ void block(const Bases& bs, const Item& cur, const Item& nxt, char* lds, Seam& S, const int tid_in) {
;     ...
;     if (NT > 1) { SLOAD_H(cur, KBASE(1)); }
;     SBAR(); qkt<0>(pA0, pA1, K_lds, bias_l, r32, hi, S.qr);
;     MASKT(pA0, pA1, 0); partialSM(pA0, pA1, m_reg, mnA, alA);
.LBB0_241:
	v_and_b32_e32 v183, 63, v33
	s_andn2_b64 vcc, exec, s[10:11]
	v_lshl_or_b32 v180, v34, 7, v0
	s_waitcnt vmcnt(0)
	s_cbranch_vccnz .LBB0_244
	s_ashr_i32 s77, s76, 31
	s_lshl_b64 s[8:9], s[76:77], 22
	v_readlane_b32 s10, v255, 39
	s_add_u32 s12, s10, s8
	v_readlane_b32 s8, v255, 40
	s_addc_u32 s9, s8, s9
	s_lshl_b32 s8, s85, 6
	s_add_i32 s10, s8, 64
	s_ashr_i32 s11, s10, 31
	s_lshl_b64 s[10:11], s[10:11], 8
	s_add_u32 s10, s12, s10
	s_addc_u32 s11, s9, s11
	v_lshl_add_u64 v[0:1], v[180:181], 1, s[10:11]
	v_add_co_u32_e32 v2, vcc, 0x2000000, v0
	s_cmp_gt_u32 s86, 63
	s_nop 0
	v_addc_co_u32_e32 v3, vcc, 0, v1, vcc
	v_add_co_u32_e32 v4, vcc, 0x2002000, v0
	global_load_dwordx4 v[96:99], v[2:3], off
	global_load_dwordx4 v[100:103], v[0:1], off
	v_addc_co_u32_e32 v5, vcc, 0, v1, vcc
	v_add_co_u32_e32 v0, vcc, 0x2000, v0
	s_nop 1
	v_addc_co_u32_e32 v1, vcc, 0, v1, vcc
	global_load_dwordx4 v[104:107], v[4:5], off
	global_load_dwordx4 v[108:111], v[0:1], off
	s_cbranch_scc1 .LBB0_244
	s_lshl_b64 s[10:11], s[76:77], 17
	v_readlane_b32 s9, v255, 34
	s_add_u32 s12, s9, s10
	s_addc_u32 s13, s81, s11
	s_ashr_i32 s9, s8, 31
	s_lshl_b64 s[10:11], s[8:9], 3
	s_add_u32 s10, s12, s10
	s_addc_u32 s11, s13, s11
	v_lshlrev_b32_e32 v0, 3, v183
	global_load_dwordx2 v[188:189], v0, s[10:11] offset:512
.LBB0_244:
	s_ashr_i32 s10, s86, 6
	v_lshrrev_b32_e32 v206, 5, v183
	s_lshl_b32 s14, s10, 5
	v_and_b32_e32 v185, 31, v33
	s_mov_b32 s12, s14
	v_lshlrev_b32_e32 v32, 2, v206
	v_writelane_b32 v255, s12, 51
	s_add_i32 s84, s14, s18
	v_sub_u32_e32 v0, v185, v32
	v_writelane_b32 v255, s13, 52
	v_add_u32_e32 v210, s84, v0
	v_lshlrev_b32_e32 v40, 4, v206
	v_add_u32_e32 v0, 0, v40
	v_add_u32_e32 v219, 0x10800, v0
	v_lshlrev_b32_e32 v0, 4, v33
	v_and_b32_e32 v41, 0x70, v0
	v_lshlrev_b32_e32 v211, 8, v185
	v_xad_u32 v0, v40, v41, 0
	v_add_u32_e32 v214, v0, v211
	ds_read_b128 v[4:7], v214 offset:32768
	ds_read_b128 v[16:19], v219
	ds_read_b128 v[20:23], v219 offset:32
	ds_read_b128 v[24:27], v219 offset:64
	ds_read_b128 v[28:31], v219 offset:96
	ds_read_b128 v[0:3], v219 offset:128
	ds_read_b128 v[36:39], v214 offset:40960
	s_waitcnt lgkmcnt(2)
	v_mfma_f32_32x32x16_bf16 v[16:31], v[4:7], v[156:159], v[16:31]
	ds_read_b128 v[4:7], v219 offset:160
	ds_read_b128 v[8:11], v219 offset:192
	ds_read_b128 v[12:15], v219 offset:224
	v_or_b32_e32 v42, 32, v40
	v_xad_u32 v42, v42, v41, 0
	v_add_u32_e32 v215, v42, v211
	v_or_b32_e32 v42, 64, v40
	v_xad_u32 v42, v42, v41, 0
	v_add_u32_e32 v213, v42, v211
	s_waitcnt lgkmcnt(0)
	v_mfma_f32_32x32x16_bf16 v[0:15], v[36:39], v[156:159], v[0:15]
	ds_read_b128 v[36:39], v215 offset:32768
	v_or_b32_e32 v40, 0x60, v40
	v_xad_u32 v40, v40, v41, 0
	v_add_u32_e32 v212, v40, v211
	s_or_b32 s9, s8, 63
	v_writelane_b32 v255, s10, 53
	s_cmp_le_i32 s9, s84
	s_waitcnt lgkmcnt(0)
	v_mfma_f32_32x32x16_bf16 v[16:31], v[36:39], v[152:155], v[16:31]
	ds_read_b128 v[36:39], v215 offset:40960
	v_writelane_b32 v255, s11, 54
	s_waitcnt lgkmcnt(0)
	v_mfma_f32_32x32x16_bf16 v[0:15], v[36:39], v[152:155], v[0:15]
	ds_read_b128 v[36:39], v213 offset:32768
	s_waitcnt lgkmcnt(0)
	v_mfma_f32_32x32x16_bf16 v[16:31], v[36:39], v[148:151], v[16:31]
	ds_read_b128 v[36:39], v213 offset:40960
	s_waitcnt lgkmcnt(0)
	v_mfma_f32_32x32x16_bf16 v[0:15], v[36:39], v[148:151], v[0:15]
	ds_read_b128 v[36:39], v212 offset:32768
	s_waitcnt lgkmcnt(0)
	v_mfma_f32_32x32x16_bf16 v[16:31], v[36:39], v[144:147], v[16:31]
	ds_read_b128 v[36:39], v212 offset:40960
	s_waitcnt lgkmcnt(0)
	v_mfma_f32_32x32x16_bf16 v[0:15], v[36:39], v[144:147], v[0:15]
	ds_read_b128 v[36:39], v214 offset:32896
	s_waitcnt lgkmcnt(0)
	v_mfma_f32_32x32x16_bf16 v[16:31], v[36:39], v[140:143], v[16:31]
	ds_read_b128 v[36:39], v214 offset:41088
	s_waitcnt lgkmcnt(0)
	v_mfma_f32_32x32x16_bf16 v[0:15], v[36:39], v[140:143], v[0:15]
	ds_read_b128 v[36:39], v215 offset:32896
	s_waitcnt lgkmcnt(0)
	v_mfma_f32_32x32x16_bf16 v[16:31], v[36:39], v[136:139], v[16:31]
	ds_read_b128 v[36:39], v215 offset:41088
	s_waitcnt lgkmcnt(0)
	v_mfma_f32_32x32x16_bf16 v[0:15], v[36:39], v[136:139], v[0:15]
	ds_read_b128 v[36:39], v213 offset:32896
	s_waitcnt lgkmcnt(0)
	v_mfma_f32_32x32x16_bf16 v[16:31], v[36:39], v[132:135], v[16:31]
	ds_read_b128 v[36:39], v213 offset:41088
	s_waitcnt lgkmcnt(0)
	v_mfma_f32_32x32x16_bf16 v[0:15], v[36:39], v[132:135], v[0:15]
	ds_read_b128 v[36:39], v212 offset:32896
	s_waitcnt lgkmcnt(0)
	v_mfma_f32_32x32x16_bf16 v[16:31], v[36:39], v[128:131], v[16:31]
	ds_read_b128 v[36:39], v212 offset:41088
	s_waitcnt lgkmcnt(0)
	v_mfma_f32_32x32x16_bf16 v[0:15], v[36:39], v[128:131], v[0:15]
	s_cbranch_scc1 .LBB0_246
; __device__ __forceinline__ void mask_tile(f32x16& p0, f32x16& p1, int dq, unsigned W) {
;     const float NEG = -__builtin_inff();
; #pragma unroll
;     for (int r = 0; r < 16; ++r) {
;         const int c = (r & 3) + 8 * (r >> 2);
;         if ((unsigned)(dq - c) >= W) p0[r] = NEG;
;         if ((unsigned)(dq - c - 32) >= W) p1[r] = NEG;
;     }
; }
	v_subrev_u32_e32 v36, s8, v210
	v_cmp_gt_i32_e64 s[68:69], 26, v36
	v_cmp_gt_i32_e64 s[70:71], 27, v36
	v_cmp_gt_i32_e64 s[66:67], 25, v36
	s_and_b64 s[68:69], s[70:71], s[68:69]
	v_cmp_gt_i32_e64 s[64:65], 24, v36
	s_and_b64 s[66:67], s[68:69], s[66:67]
	v_cmp_gt_i32_e64 s[62:63], 19, v36
	s_and_b64 s[64:65], s[66:67], s[64:65]
	v_cmp_gt_i32_e64 s[60:61], 18, v36
	s_and_b64 s[62:63], s[64:65], s[62:63]
	v_cmp_gt_i32_e64 s[58:59], 17, v36
	s_and_b64 s[60:61], s[62:63], s[60:61]
	v_cmp_gt_i32_e64 s[56:57], 16, v36
	s_and_b64 s[58:59], s[60:61], s[58:59]
	v_cmp_gt_i32_e64 s[54:55], 11, v36
	s_and_b64 s[56:57], s[58:59], s[56:57]
	v_cmp_gt_i32_e64 s[52:53], 10, v36
	s_and_b64 s[54:55], s[56:57], s[54:55]
	v_cmp_gt_i32_e64 s[50:51], 9, v36
	s_and_b64 s[52:53], s[54:55], s[52:53]
	v_cmp_gt_i32_e64 s[48:49], 8, v36
	s_and_b64 s[50:51], s[52:53], s[50:51]
	v_cmp_gt_i32_e64 s[46:47], 3, v36
	s_and_b64 s[48:49], s[50:51], s[48:49]
	v_cmp_gt_i32_e64 s[44:45], 2, v36
	s_and_b64 s[46:47], s[48:49], s[46:47]
	v_cmp_gt_i32_e64 s[40:41], 1, v36
	s_and_b64 s[44:45], s[46:47], s[44:45]
	v_cmp_gt_i32_e64 s[38:39], 0, v36
	s_and_b64 s[40:41], s[44:45], s[40:41]
	s_and_b64 s[38:39], s[40:41], s[38:39]
	v_cmp_gt_i32_e64 s[36:37], 58, v36
	v_cndmask_b32_e64 v16, v16, v205, s[38:39]
	v_cmp_gt_i32_e64 s[38:39], 59, v36
	v_cmp_gt_i32_e64 s[34:35], 57, v36
	s_and_b64 s[36:37], s[38:39], s[36:37]
	v_cmp_gt_i32_e64 s[30:31], 56, v36
	s_and_b64 s[34:35], s[36:37], s[34:35]
	v_cmp_gt_i32_e64 s[28:29], 51, v36
	s_and_b64 s[30:31], s[34:35], s[30:31]
	v_cmp_gt_i32_e64 s[26:27], 50, v36
	s_and_b64 s[28:29], s[30:31], s[28:29]
	v_cmp_gt_i32_e64 s[24:25], 49, v36
	s_and_b64 s[26:27], s[28:29], s[26:27]
	v_cmp_gt_i32_e64 s[22:23], 48, v36
	s_and_b64 s[24:25], s[26:27], s[24:25]
	v_cmp_gt_i32_e64 s[20:21], 43, v36
	s_and_b64 s[22:23], s[24:25], s[22:23]
	v_cmp_gt_i32_e64 s[18:19], 42, v36
	s_and_b64 s[20:21], s[22:23], s[20:21]
	v_cmp_gt_i32_e64 s[16:17], 41, v36
	s_and_b64 s[18:19], s[20:21], s[18:19]
	v_cmp_gt_i32_e64 s[14:15], 40, v36
	s_and_b64 s[16:17], s[18:19], s[16:17]
	v_cmp_gt_i32_e64 s[12:13], 35, v36
	s_and_b64 s[14:15], s[16:17], s[14:15]
	v_cmp_gt_i32_e64 s[10:11], 34, v36
	s_and_b64 s[12:13], s[14:15], s[12:13]
	v_cmp_gt_i32_e64 s[8:9], 33, v36
	s_and_b64 s[10:11], s[12:13], s[10:11]
	v_cmp_gt_i32_e32 vcc, 32, v36
	s_and_b64 s[8:9], s[10:11], s[8:9]
	s_and_b64 vcc, s[8:9], vcc
	v_cndmask_b32_e64 v31, v31, v205, s[70:71]
	v_cndmask_b32_e64 v30, v30, v205, s[68:69]
	v_cndmask_b32_e64 v29, v29, v205, s[66:67]
	v_cndmask_b32_e64 v28, v28, v205, s[64:65]
	v_cndmask_b32_e64 v27, v27, v205, s[62:63]
	v_cndmask_b32_e64 v26, v26, v205, s[60:61]
	v_cndmask_b32_e64 v25, v25, v205, s[58:59]
	v_cndmask_b32_e64 v24, v24, v205, s[56:57]
	v_cndmask_b32_e64 v23, v23, v205, s[54:55]
	v_readlane_b32 s54, v255, 30
	v_cndmask_b32_e64 v22, v22, v205, s[52:53]
	v_cndmask_b32_e64 v21, v21, v205, s[50:51]
	v_cndmask_b32_e64 v20, v20, v205, s[48:49]
	v_cndmask_b32_e64 v19, v19, v205, s[46:47]
	v_cndmask_b32_e64 v18, v18, v205, s[44:45]
	v_cndmask_b32_e64 v17, v17, v205, s[40:41]
	v_cndmask_b32_e64 v15, v15, v205, s[38:39]
	v_cndmask_b32_e64 v14, v14, v205, s[36:37]
	v_cndmask_b32_e64 v13, v13, v205, s[34:35]
	v_cndmask_b32_e64 v12, v12, v205, s[30:31]
	v_cndmask_b32_e64 v11, v11, v205, s[28:29]
	v_cndmask_b32_e64 v10, v10, v205, s[26:27]
	v_cndmask_b32_e64 v9, v9, v205, s[24:25]
	v_cndmask_b32_e64 v8, v8, v205, s[22:23]
	v_cndmask_b32_e64 v7, v7, v205, s[20:21]
	v_cndmask_b32_e64 v6, v6, v205, s[18:19]
	v_cndmask_b32_e64 v5, v5, v205, s[16:17]
	v_cndmask_b32_e64 v4, v4, v205, s[14:15]
	v_cndmask_b32_e64 v3, v3, v205, s[12:13]
	v_cndmask_b32_e64 v2, v2, v205, s[10:11]
	v_cndmask_b32_e64 v1, v1, v205, s[8:9]
	v_cndmask_b32_e32 v0, v0, v205, vcc
	v_readlane_b32 s55, v255, 31

; __device__ __forceinline__ void finishSM(f32x16& p0, f32x16& p1, float alpha, float& l_reg, bf16x8& pa0, bf16x8& pa1, bf16x8& pa2, bf16x8& pa3) {
;     for (int r = 0; r < 16; ++r) p1[r] = __builtin_amdgcn_exp2f(p1[r]);
;     float ps = 0; for (int r = 0; r < 16; ++r) ps += p0[r]; for (int r = 0; r < 16; ++r) ps += p1[r];
;     { auto rr = __builtin_amdgcn_permlane32_swap(__float_as_uint(ps), __float_as_uint(ps), false, false);
;       ps = __uint_as_float(rr[0]) + __uint_as_float(rr[1]); }
;     l_reg = l_reg * alpha + ps;
;     ...
;     PK4(p0, 0, pa0); PK4(p0, 8, pa1); PK4(p1, 0, pa2); PK4(p1, 8, pa3);
;     ...
; }
; template <int KB>
; __device__ __forceinline__ void qkt(f32x16& p0, f32x16& p1, const char* K_lds, const float* bias_l, int r32, int hi, const bf16x8* qr) {
;     const f32x4* bl = reinterpret_cast<const f32x4*>(bias_l + KB * 64);
; #pragma unroll
;     for (int g = 0; g < 4; ++g) { const f32x4 b0 = bl[2 * g + hi], b1 = bl[8 + 2 * g + hi];
;         p0[4 * g + 0] = b0[0]; p0[4 * g + 1] = b0[1]; p0[4 * g + 2] = b0[2]; p0[4 * g + 3] = b0[3];
;         p1[4 * g + 0] = b1[0]; p1[4 * g + 1] = b1[1]; p1[4 * g + 2] = b1[2]; p1[4 * g + 3] = b1[3]; }
;     const char* kb[4];
; #pragma unroll
;     for (int dd = 0; dd < 4; ++dd) kb[dd] = K_lds + KB * SHM_K + KSWZ(r32, (dd * 16 + hi * 8) * 2);
; #pragma unroll
;     for (int d0 = 0; d0 < 8; ++d0) { const char* a = kb[d0 & 3] + (d0 >> 2) * 128;
;         bf16x8 b0 = *reinterpret_cast<const bf16x8*>(a);
;         bf16x8 b1 = *reinterpret_cast<const bf16x8*>(a + 32 * 256);
;         p0 = __builtin_amdgcn_mfma_f32_32x32x16_bf16(b0, qr[d0], p0, 0, 0, 0);
;         p1 = __builtin_amdgcn_mfma_f32_32x32x16_bf16(b1, qr[d0], p1, 0, 0, 0); }
; }
.LBB0_255:
	ds_read_b128 v[84:87], v220
	ds_read_b128 v[88:91], v220 offset:32
	ds_read_b128 v[68:71], v220 offset:128
	ds_read_b128 v[72:75], v220 offset:160
	ds_read_b128 v[92:95], v220 offset:64
	ds_read_b128 v[76:79], v220 offset:192
	ds_read_b128 v[96:99], v220 offset:96
	ds_read_b128 v[80:83], v220 offset:224
	ds_read_b128 v[196:199], v214 offset:49152
	ds_read_b128 v[242:245], v214 offset:57344
	ds_read_b128 v[246:249], v215 offset:49152
	ds_read_b128 v[250:253], v215 offset:57344
	v_exp_f32_e32 v104, v126
	v_exp_f32_e32 v105, v127
	v_exp_f32_e32 v106, v124
	v_exp_f32_e32 v107, v125
	v_exp_f32_e32 v108, v122
	v_exp_f32_e32 v109, v123
	v_exp_f32_e32 v110, v120
	v_exp_f32_e32 v111, v121
	v_exp_f32_e32 v118, v118
	v_exp_f32_e32 v119, v119
	v_exp_f32_e32 v116, v116
	v_exp_f32_e32 v117, v117
	v_exp_f32_e32 v114, v114
	v_exp_f32_e32 v115, v115
	v_exp_f32_e32 v112, v112
	v_exp_f32_e32 v113, v113
	v_add_f32_e32 v64, 0, v237
	v_add_f32_e32 v64, v239, v64
	v_add_f32_e32 v64, v235, v64
	v_add_f32_e32 v64, v238, v64
	v_add_f32_e32 v64, v234, v64
	v_add_f32_e32 v64, v236, v64
	v_add_f32_e32 v64, v232, v64
	v_add_f32_e32 v64, v233, v64
	v_add_f32_e32 v64, v228, v64
	v_add_f32_e32 v64, v231, v64
	v_add_f32_e32 v64, v179, v64
	v_add_f32_e32 v64, v229, v64
	s_waitcnt lgkmcnt(2)
	v_mfma_f32_32x32x16_bf16 v[84:99], v[196:199], v[156:159], v[84:99]
	v_add_f32_e32 v64, v177, v64
	v_add_f32_e32 v64, v230, v64
	v_add_f32_e32 v64, v178, v64
	v_mfma_f32_32x32x16_bf16 v[68:83], v[242:245], v[156:159], v[68:83]
	v_add_f32_e32 v64, v227, v64
	v_add_f32_e32 v64, v104, v64
	v_add_f32_e32 v64, v105, v64
	ds_read_b128 v[196:199], v213 offset:49152
	ds_read_b128 v[242:245], v213 offset:57344
	s_waitcnt lgkmcnt(2)
	v_mfma_f32_32x32x16_bf16 v[84:99], v[246:249], v[152:155], v[84:99]
	v_add_f32_e32 v64, v106, v64
	v_add_f32_e32 v64, v107, v64
	v_add_f32_e32 v64, v108, v64
	v_mfma_f32_32x32x16_bf16 v[68:83], v[250:253], v[152:155], v[68:83]
	v_add_f32_e32 v64, v109, v64
	v_add_f32_e32 v64, v110, v64
	v_add_f32_e32 v64, v111, v64
	ds_read_b128 v[246:249], v212 offset:49152
	ds_read_b128 v[250:253], v212 offset:57344
	s_waitcnt lgkmcnt(2)
	v_mfma_f32_32x32x16_bf16 v[84:99], v[196:199], v[148:151], v[84:99]
	v_add_f32_e32 v64, v118, v64
	v_add_f32_e32 v64, v119, v64
	v_add_f32_e32 v64, v116, v64
	v_mfma_f32_32x32x16_bf16 v[68:83], v[242:245], v[148:151], v[68:83]
	v_add_f32_e32 v64, v117, v64
	v_add_f32_e32 v64, v114, v64
	v_add_f32_e32 v64, v115, v64
	ds_read_b128 v[196:199], v214 offset:49280
	ds_read_b128 v[242:245], v214 offset:57472
	s_waitcnt lgkmcnt(2)
	v_mfma_f32_32x32x16_bf16 v[84:99], v[246:249], v[144:147], v[84:99]
	v_add_f32_e32 v64, v112, v64
	v_add_f32_e32 v224, v113, v64
	v_mov_b32_e32 v225, v224
	v_mfma_f32_32x32x16_bf16 v[68:83], v[250:253], v[144:147], v[68:83]
	v_cvt_pk_bf16_f32 v64, v237, v239
	v_cvt_pk_bf16_f32 v65, v235, v238
	v_cvt_pk_bf16_f32 v66, v234, v236
	ds_read_b128 v[246:249], v215 offset:49280
	ds_read_b128 v[250:253], v215 offset:57472
	s_waitcnt lgkmcnt(2)
	v_mfma_f32_32x32x16_bf16 v[84:99], v[196:199], v[140:143], v[84:99]
	v_cvt_pk_bf16_f32 v67, v232, v233
	v_cvt_pk_bf16_f32 v100, v228, v231
	v_cvt_pk_bf16_f32 v101, v179, v229
	v_mfma_f32_32x32x16_bf16 v[68:83], v[242:245], v[140:143], v[68:83]
	v_cvt_pk_bf16_f32 v102, v177, v230
	v_cvt_pk_bf16_f32 v103, v178, v227
	v_cvt_pk_bf16_f32 v104, v104, v105
	ds_read_b128 v[196:199], v213 offset:49280
	ds_read_b128 v[242:245], v213 offset:57472
	s_waitcnt lgkmcnt(2)
	v_mfma_f32_32x32x16_bf16 v[84:99], v[246:249], v[136:139], v[84:99]
	v_cvt_pk_bf16_f32 v105, v106, v107
	v_cvt_pk_bf16_f32 v106, v108, v109
	v_cvt_pk_bf16_f32 v107, v110, v111
	v_mfma_f32_32x32x16_bf16 v[68:83], v[250:253], v[136:139], v[68:83]
	v_cvt_pk_bf16_f32 v108, v118, v119
	v_cvt_pk_bf16_f32 v109, v116, v117
	v_cvt_pk_bf16_f32 v110, v114, v115
	ds_read_b128 v[246:249], v212 offset:49280
	ds_read_b128 v[250:253], v212 offset:57472
	s_waitcnt lgkmcnt(2)
	v_mfma_f32_32x32x16_bf16 v[84:99], v[196:199], v[132:135], v[84:99]
	v_cvt_pk_bf16_f32 v111, v112, v113
	v_permlane32_swap_b32_e32 v224, v225
	v_permlane32_swap_b32_e32 v64, v66
	v_mfma_f32_32x32x16_bf16 v[68:83], v[242:245], v[132:135], v[68:83]
	v_permlane32_swap_b32_e32 v65, v67
	v_permlane32_swap_b32_e32 v100, v102
	v_permlane32_swap_b32_e32 v101, v103
	ds_read_b64_tr_b16 v[112:113], v209 offset:0x0
	ds_read_b64_tr_b16 v[114:115], v209 offset:0x800
	ds_read_b64_tr_b16 v[116:117], v209 offset:0x1000
	ds_read_b64_tr_b16 v[118:119], v209 offset:0x1800
	ds_read_b64_tr_b16 v[120:121], v209 offset:0x2000
	ds_read_b64_tr_b16 v[122:123], v209 offset:0x2800
	ds_read_b64_tr_b16 v[124:125], v209 offset:0x3000
	ds_read_b64_tr_b16 v[126:127], v209 offset:0x3800
	s_waitcnt lgkmcnt(8)
	v_mfma_f32_32x32x16_bf16 v[84:99], v[246:249], v[128:131], v[84:99]
	v_permlane32_swap_b32_e32 v104, v106
	v_permlane32_swap_b32_e32 v105, v107
	v_permlane32_swap_b32_e32 v108, v110
	v_mfma_f32_32x32x16_bf16 v[68:83], v[250:253], v[128:131], v[68:83]
	v_permlane32_swap_b32_e32 v109, v111
	s_add_i32 s12, s96, 0xffffffbf
	s_cmp_le_i32 s12, s84
	s_cbranch_scc1 .Lhs1_nomask
; __device__ __forceinline__ void mask_tile(f32x16& p0, f32x16& p1, int dq, unsigned W) {
;     const float NEG = -__builtin_inff();
; #pragma unroll
;     for (int r = 0; r < 16; ++r) {
;         const int c = (r & 3) + 8 * (r >> 2);
;         if ((unsigned)(dq - c) >= W) p0[r] = NEG;
;         if ((unsigned)(dq - c - 32) >= W) p1[r] = NEG;
;     }
; }
	v_add_u32_e32 v250, 64, v223
	v_cmp_gt_i32_e64 s[72:73], 26, v250
	v_cmp_gt_i32_e64 s[74:75], 27, v250
	v_cmp_gt_i32_e64 s[70:71], 25, v250
	s_and_b64 s[72:73], s[74:75], s[72:73]
	v_cmp_gt_i32_e64 s[68:69], 24, v250
	s_and_b64 s[70:71], s[72:73], s[70:71]
	v_cmp_gt_i32_e64 s[66:67], 19, v250
	s_and_b64 s[68:69], s[70:71], s[68:69]
	v_cmp_gt_i32_e64 s[64:65], 18, v250
	s_and_b64 s[66:67], s[68:69], s[66:67]
	v_cmp_gt_i32_e64 s[62:63], 17, v250
	s_and_b64 s[64:65], s[66:67], s[64:65]
	v_cmp_gt_i32_e64 s[60:61], 16, v250
	s_and_b64 s[62:63], s[64:65], s[62:63]
	v_cmp_gt_i32_e64 s[58:59], 11, v250
	s_and_b64 s[60:61], s[62:63], s[60:61]
	v_cmp_gt_i32_e64 s[56:57], 10, v250
	s_and_b64 s[58:59], s[60:61], s[58:59]
	v_cmp_gt_i32_e64 s[54:55], 9, v250
	s_and_b64 s[56:57], s[58:59], s[56:57]
	v_cmp_gt_i32_e64 s[52:53], 8, v250
	s_and_b64 s[54:55], s[56:57], s[54:55]
	v_cmp_gt_i32_e64 s[50:51], 3, v250
	s_and_b64 s[52:53], s[54:55], s[52:53]
	v_cmp_gt_i32_e64 s[48:49], 2, v250
	s_and_b64 s[50:51], s[52:53], s[50:51]
	v_cmp_gt_i32_e64 s[46:47], 1, v250
	s_and_b64 s[48:49], s[50:51], s[48:49]
	v_cmp_gt_i32_e64 s[44:45], 0, v250
	s_and_b64 s[46:47], s[48:49], s[46:47]
	s_and_b64 s[44:45], s[46:47], s[44:45]
	v_cmp_gt_i32_e64 s[40:41], 58, v250
	v_cndmask_b32_e64 v84, v84, v205, s[44:45]
	v_cmp_gt_i32_e64 s[44:45], 59, v250
	v_cmp_gt_i32_e64 s[38:39], 57, v250
	s_and_b64 s[40:41], s[44:45], s[40:41]
	v_cmp_gt_i32_e64 s[36:37], 56, v250
	s_and_b64 s[38:39], s[40:41], s[38:39]
	v_cmp_gt_i32_e64 s[34:35], 51, v250
	s_and_b64 s[36:37], s[38:39], s[36:37]
	v_cmp_gt_i32_e64 s[30:31], 50, v250
	s_and_b64 s[34:35], s[36:37], s[34:35]
	v_cmp_gt_i32_e64 s[28:29], 49, v250
	s_and_b64 s[30:31], s[34:35], s[30:31]
	v_cmp_gt_i32_e64 s[26:27], 48, v250
	s_and_b64 s[28:29], s[30:31], s[28:29]
	v_cmp_gt_i32_e64 s[24:25], 43, v250
	s_and_b64 s[26:27], s[28:29], s[26:27]
	v_cmp_gt_i32_e64 s[22:23], 42, v250
	s_and_b64 s[24:25], s[26:27], s[24:25]
	v_cmp_gt_i32_e64 s[20:21], 41, v250
	s_and_b64 s[22:23], s[24:25], s[22:23]
	v_cmp_gt_i32_e64 s[18:19], 40, v250
	s_and_b64 s[20:21], s[22:23], s[20:21]
	v_cmp_gt_i32_e64 s[16:17], 35, v250
	s_and_b64 s[18:19], s[20:21], s[18:19]
	v_cmp_gt_i32_e64 s[14:15], 34, v250
	s_and_b64 s[16:17], s[18:19], s[16:17]
	v_cmp_gt_i32_e64 s[12:13], 33, v250
	s_and_b64 s[14:15], s[16:17], s[14:15]
	v_cmp_gt_i32_e32 vcc, 32, v250
	s_and_b64 s[12:13], s[14:15], s[12:13]
	s_and_b64 vcc, s[12:13], vcc
	v_cndmask_b32_e64 v99, v99, v205, s[74:75]
	v_cndmask_b32_e64 v98, v98, v205, s[72:73]
	v_cndmask_b32_e64 v97, v97, v205, s[70:71]
	v_cndmask_b32_e64 v96, v96, v205, s[68:69]
	v_cndmask_b32_e64 v95, v95, v205, s[66:67]
	v_cndmask_b32_e64 v94, v94, v205, s[64:65]
	v_cndmask_b32_e64 v93, v93, v205, s[62:63]
	v_cndmask_b32_e64 v92, v92, v205, s[60:61]
	v_cndmask_b32_e64 v91, v91, v205, s[58:59]
	v_cndmask_b32_e64 v90, v90, v205, s[56:57]
	v_cndmask_b32_e64 v89, v89, v205, s[54:55]
	v_cndmask_b32_e64 v88, v88, v205, s[52:53]
	v_cndmask_b32_e64 v87, v87, v205, s[50:51]
	v_cndmask_b32_e64 v86, v86, v205, s[48:49]
	v_cndmask_b32_e64 v85, v85, v205, s[46:47]
	v_cndmask_b32_e64 v83, v83, v205, s[44:45]
	v_cndmask_b32_e64 v82, v82, v205, s[40:41]
	v_cndmask_b32_e64 v81, v81, v205, s[38:39]
	v_cndmask_b32_e64 v80, v80, v205, s[36:37]
	v_cndmask_b32_e64 v79, v79, v205, s[34:35]
	v_cndmask_b32_e64 v78, v78, v205, s[30:31]
	v_cndmask_b32_e64 v77, v77, v205, s[28:29]
	v_cndmask_b32_e64 v76, v76, v205, s[26:27]
	v_cndmask_b32_e64 v75, v75, v205, s[24:25]
	v_cndmask_b32_e64 v74, v74, v205, s[22:23]
	v_cndmask_b32_e64 v73, v73, v205, s[20:21]
	v_cndmask_b32_e64 v72, v72, v205, s[18:19]
	v_cndmask_b32_e64 v71, v71, v205, s[16:17]
	v_cndmask_b32_e64 v70, v70, v205, s[14:15]
	v_cndmask_b32_e64 v69, v69, v205, s[12:13]
	v_cndmask_b32_e32 v68, v68, v205, vcc
	v_readlane_b32 s54, v255, 30
	v_readlane_b32 s55, v255, 31

; __device__ __forceinline__ void finishSM(f32x16& p0, f32x16& p1, float alpha, float& l_reg, bf16x8& pa0, bf16x8& pa1, bf16x8& pa2, bf16x8& pa3) {
;     for (int r = 0; r < 16; ++r) p1[r] = __builtin_amdgcn_exp2f(p1[r]);
;     float ps = 0; for (int r = 0; r < 16; ++r) ps += p0[r]; for (int r = 0; r < 16; ++r) ps += p1[r];
;     { auto rr = __builtin_amdgcn_permlane32_swap(__float_as_uint(ps), __float_as_uint(ps), false, false);
;       ps = __uint_as_float(rr[0]) + __uint_as_float(rr[1]); }
;     l_reg = l_reg * alpha + ps;
;     ...
;     PK4(p0, 0, pa0); PK4(p0, 8, pa1); PK4(p1, 0, pa2); PK4(p1, 8, pa3);
;     ...
; }
; template <int KB>
; __device__ __forceinline__ void qkt(f32x16& p0, f32x16& p1, const char* K_lds, const float* bias_l, int r32, int hi, const bf16x8* qr) {
;     const f32x4* bl = reinterpret_cast<const f32x4*>(bias_l + KB * 64);
; #pragma unroll
;     for (int g = 0; g < 4; ++g) { const f32x4 b0 = bl[2 * g + hi], b1 = bl[8 + 2 * g + hi];
;         p0[4 * g + 0] = b0[0]; p0[4 * g + 1] = b0[1]; p0[4 * g + 2] = b0[2]; p0[4 * g + 3] = b0[3];
;         p1[4 * g + 0] = b1[0]; p1[4 * g + 1] = b1[1]; p1[4 * g + 2] = b1[2]; p1[4 * g + 3] = b1[3]; }
;     const char* kb[4];
; #pragma unroll
;     for (int dd = 0; dd < 4; ++dd) kb[dd] = K_lds + KB * SHM_K + KSWZ(r32, (dd * 16 + hi * 8) * 2);
; #pragma unroll
;     for (int d0 = 0; d0 < 8; ++d0) { const char* a = kb[d0 & 3] + (d0 >> 2) * 128;
;         bf16x8 b0 = *reinterpret_cast<const bf16x8*>(a);
;         bf16x8 b1 = *reinterpret_cast<const bf16x8*>(a + 32 * 256);
;         p0 = __builtin_amdgcn_mfma_f32_32x32x16_bf16(b0, qr[d0], p0, 0, 0, 0);
;         p1 = __builtin_amdgcn_mfma_f32_32x32x16_bf16(b1, qr[d0], p1, 0, 0, 0); }
; }
; template <int VB>
; __device__ __forceinline__ void pv_tile(f32x16* o, int vb0, bf16x8 pa0, bf16x8 pa1, bf16x8 pa2, bf16x8 pa3) {
.LBB0_267:
	ds_read_b128 v[112:115], v219
	ds_read_b128 v[116:119], v219 offset:32
	ds_read_b128 v[96:99], v219 offset:128
	ds_read_b128 v[100:103], v219 offset:160
	ds_read_b128 v[120:123], v219 offset:64
	ds_read_b128 v[104:107], v219 offset:192
	ds_read_b128 v[124:127], v219 offset:96
	ds_read_b128 v[108:111], v219 offset:224
	ds_read_b128 v[196:199], v214 offset:32768
	ds_read_b128 v[242:245], v214 offset:40960
	ds_read_b128 v[246:249], v215 offset:32768
	ds_read_b128 v[250:253], v215 offset:40960
	v_exp_f32_e32 v85, v85
	v_exp_f32_e32 v86, v86
	v_exp_f32_e32 v87, v87
	v_exp_f32_e32 v88, v88
	v_exp_f32_e32 v89, v89
	v_exp_f32_e32 v90, v90
	v_exp_f32_e32 v91, v91
	v_exp_f32_e32 v92, v92
	v_exp_f32_e32 v83, v95
	v_exp_f32_e32 v95, v176
	v_exp_f32_e32 v80, v84
	v_exp_f32_e32 v81, v93
	v_exp_f32_e32 v82, v94
	v_exp_f32_e32 v84, v177
	v_exp_f32_e32 v93, v178
	v_exp_f32_e32 v94, v179
	v_add_f32_e32 v176, 0, v64
	v_add_f32_e32 v176, v65, v176
	v_add_f32_e32 v176, v66, v176
	v_add_f32_e32 v176, v67, v176
	v_add_f32_e32 v176, v68, v176
	v_add_f32_e32 v176, v69, v176
	v_add_f32_e32 v176, v70, v176
	v_add_f32_e32 v176, v71, v176
	v_add_f32_e32 v176, v72, v176
	v_add_f32_e32 v176, v73, v176
	v_add_f32_e32 v176, v74, v176
	v_add_f32_e32 v176, v75, v176
	s_waitcnt lgkmcnt(2)
	v_mfma_f32_32x32x16_bf16 v[112:127], v[196:199], v[156:159], v[112:127]
	v_add_f32_e32 v176, v76, v176
	v_add_f32_e32 v176, v77, v176
	v_add_f32_e32 v176, v78, v176
	v_mfma_f32_32x32x16_bf16 v[96:111], v[242:245], v[156:159], v[96:111]
	v_add_f32_e32 v176, v79, v176
	v_add_f32_e32 v176, v80, v176
	v_add_f32_e32 v176, v81, v176
	ds_read_b128 v[196:199], v213 offset:32768
	ds_read_b128 v[242:245], v213 offset:40960
	s_waitcnt lgkmcnt(2)
	v_mfma_f32_32x32x16_bf16 v[112:127], v[246:249], v[152:155], v[112:127]
	v_add_f32_e32 v176, v82, v176
	v_add_f32_e32 v176, v83, v176
	v_add_f32_e32 v176, v84, v176
	v_mfma_f32_32x32x16_bf16 v[96:111], v[250:253], v[152:155], v[96:111]
	v_add_f32_e32 v176, v85, v176
	v_add_f32_e32 v176, v86, v176
	v_add_f32_e32 v176, v87, v176
	ds_read_b128 v[246:249], v212 offset:32768
	ds_read_b128 v[250:253], v212 offset:40960
	s_waitcnt lgkmcnt(2)
	v_mfma_f32_32x32x16_bf16 v[112:127], v[196:199], v[148:151], v[112:127]
	v_add_f32_e32 v176, v88, v176
	v_add_f32_e32 v176, v89, v176
	v_add_f32_e32 v176, v90, v176
	v_mfma_f32_32x32x16_bf16 v[96:111], v[242:245], v[148:151], v[96:111]
	v_add_f32_e32 v176, v91, v176
	v_add_f32_e32 v176, v92, v176
	v_add_f32_e32 v176, v93, v176
	ds_read_b128 v[196:199], v214 offset:32896
	ds_read_b128 v[242:245], v214 offset:41088
	s_waitcnt lgkmcnt(2)
	v_mfma_f32_32x32x16_bf16 v[112:127], v[246:249], v[144:147], v[112:127]
	v_add_f32_e32 v176, v94, v176
	v_add_f32_e32 v240, v95, v176
	v_mov_b32_e32 v241, v240
	v_mfma_f32_32x32x16_bf16 v[96:111], v[250:253], v[144:147], v[96:111]
	v_cvt_pk_bf16_f32 v64, v64, v65
	v_cvt_pk_bf16_f32 v65, v66, v67
	v_cvt_pk_bf16_f32 v66, v68, v69
	ds_read_b128 v[246:249], v215 offset:32896
	ds_read_b128 v[250:253], v215 offset:41088
	s_waitcnt lgkmcnt(2)
	v_mfma_f32_32x32x16_bf16 v[112:127], v[196:199], v[140:143], v[112:127]
	v_cvt_pk_bf16_f32 v67, v70, v71
	v_cvt_pk_bf16_f32 v68, v72, v73
	v_cvt_pk_bf16_f32 v69, v74, v75
	v_mfma_f32_32x32x16_bf16 v[96:111], v[242:245], v[140:143], v[96:111]
	v_cvt_pk_bf16_f32 v70, v76, v77
	v_cvt_pk_bf16_f32 v71, v78, v79
	v_cvt_pk_bf16_f32 v72, v80, v81
	ds_read_b128 v[196:199], v213 offset:32896
	ds_read_b128 v[242:245], v213 offset:41088
	s_waitcnt lgkmcnt(2)
	v_mfma_f32_32x32x16_bf16 v[112:127], v[246:249], v[136:139], v[112:127]
	v_cvt_pk_bf16_f32 v73, v82, v83
	v_cvt_pk_bf16_f32 v74, v84, v85
	v_cvt_pk_bf16_f32 v75, v86, v87
	v_mfma_f32_32x32x16_bf16 v[96:111], v[250:253], v[136:139], v[96:111]
	v_cvt_pk_bf16_f32 v76, v88, v89
	v_cvt_pk_bf16_f32 v77, v90, v91
	v_cvt_pk_bf16_f32 v78, v92, v93
	ds_read_b128 v[246:249], v212 offset:32896
	ds_read_b128 v[250:253], v212 offset:41088
	s_waitcnt lgkmcnt(2)
	v_mfma_f32_32x32x16_bf16 v[112:127], v[196:199], v[132:135], v[112:127]
	v_cvt_pk_bf16_f32 v79, v94, v95
	v_permlane32_swap_b32_e32 v240, v241
	v_permlane32_swap_b32_e32 v64, v66
	v_mfma_f32_32x32x16_bf16 v[96:111], v[242:245], v[132:135], v[96:111]
	v_permlane32_swap_b32_e32 v65, v67
	v_permlane32_swap_b32_e32 v68, v70
	v_permlane32_swap_b32_e32 v69, v71
	ds_read_b64_tr_b16 v[196:197], v209 offset:0x4000
	ds_read_b64_tr_b16 v[198:199], v209 offset:0x4800
	ds_read_b64_tr_b16 v[242:243], v209 offset:0x5000
	ds_read_b64_tr_b16 v[244:245], v209 offset:0x5800
	s_waitcnt lgkmcnt(4)
	v_mfma_f32_32x32x16_bf16 v[112:127], v[246:249], v[128:131], v[112:127]
	v_permlane32_swap_b32_e32 v72, v74
	v_permlane32_swap_b32_e32 v73, v75
	v_permlane32_swap_b32_e32 v76, v78
	v_mfma_f32_32x32x16_bf16 v[96:111], v[250:253], v[128:131], v[96:111]
	v_permlane32_swap_b32_e32 v77, v79
	ds_read_b64_tr_b16 v[246:247], v209 offset:0x6000
	ds_read_b64_tr_b16 v[248:249], v209 offset:0x6800
	ds_read_b64_tr_b16 v[250:251], v209 offset:0x7000
	ds_read_b64_tr_b16 v[252:253], v209 offset:0x7800
	s_add_i32 s12, s96, -1
	s_cmp_le_i32 s12, s84
	s_cbranch_scc1 .Lhs2_nomask
; __device__ __forceinline__ void mask_tile(f32x16& p0, f32x16& p1, int dq, unsigned W) {
;     const float NEG = -__builtin_inff();
; #pragma unroll
;     for (int r = 0; r < 16; ++r) {
;         const int c = (r & 3) + 8 * (r >> 2);
;         if ((unsigned)(dq - c) >= W) p0[r] = NEG;
;         if ((unsigned)(dq - c - 32) >= W) p1[r] = NEG;
;     }
; }
	v_cmp_gt_i32_e64 s[72:73], 26, v223
	v_cmp_gt_i32_e64 s[74:75], 27, v223
	v_cmp_gt_i32_e64 s[70:71], 25, v223
	s_and_b64 s[72:73], s[74:75], s[72:73]
	v_cmp_gt_i32_e64 s[68:69], 24, v223
	s_and_b64 s[70:71], s[72:73], s[70:71]
	v_cmp_gt_i32_e64 s[66:67], 19, v223
	s_and_b64 s[68:69], s[70:71], s[68:69]
	v_cmp_gt_i32_e64 s[64:65], 18, v223
	s_and_b64 s[66:67], s[68:69], s[66:67]
	v_cmp_gt_i32_e64 s[62:63], 17, v223
	s_and_b64 s[64:65], s[66:67], s[64:65]
	v_cmp_gt_i32_e64 s[60:61], 16, v223
	s_and_b64 s[62:63], s[64:65], s[62:63]
	v_cmp_gt_i32_e64 s[58:59], 11, v223
	s_and_b64 s[60:61], s[62:63], s[60:61]
	v_cmp_gt_i32_e64 s[56:57], 10, v223
	s_and_b64 s[58:59], s[60:61], s[58:59]
	v_cmp_gt_i32_e64 s[54:55], 9, v223
	s_and_b64 s[56:57], s[58:59], s[56:57]
	v_cmp_gt_i32_e64 s[52:53], 8, v223
	s_and_b64 s[54:55], s[56:57], s[54:55]
	v_cmp_gt_i32_e64 s[50:51], 3, v223
	s_and_b64 s[52:53], s[54:55], s[52:53]
	v_cmp_gt_i32_e64 s[48:49], 2, v223
	s_and_b64 s[50:51], s[52:53], s[50:51]
	v_cmp_gt_i32_e64 s[46:47], 1, v223
	s_and_b64 s[48:49], s[50:51], s[48:49]
	v_cmp_gt_i32_e64 s[44:45], 0, v223
	s_and_b64 s[46:47], s[48:49], s[46:47]
	s_and_b64 s[44:45], s[46:47], s[44:45]
	v_cmp_gt_i32_e64 s[40:41], 58, v223
	v_cndmask_b32_e64 v112, v112, v205, s[44:45]
	v_cmp_gt_i32_e64 s[44:45], 59, v223
	v_cmp_gt_i32_e64 s[38:39], 57, v223
	s_and_b64 s[40:41], s[44:45], s[40:41]
	v_cmp_gt_i32_e64 s[36:37], 56, v223
	s_and_b64 s[38:39], s[40:41], s[38:39]
	v_cmp_gt_i32_e64 s[34:35], 51, v223
	s_and_b64 s[36:37], s[38:39], s[36:37]
	v_cmp_gt_i32_e64 s[30:31], 50, v223
	s_and_b64 s[34:35], s[36:37], s[34:35]
	v_cmp_gt_i32_e64 s[28:29], 49, v223
	s_and_b64 s[30:31], s[34:35], s[30:31]
	v_cmp_gt_i32_e64 s[26:27], 48, v223
	s_and_b64 s[28:29], s[30:31], s[28:29]
	v_cmp_gt_i32_e64 s[24:25], 43, v223
	s_and_b64 s[26:27], s[28:29], s[26:27]
	v_cmp_gt_i32_e64 s[22:23], 42, v223
	s_and_b64 s[24:25], s[26:27], s[24:25]
	v_cmp_gt_i32_e64 s[20:21], 41, v223
	s_and_b64 s[22:23], s[24:25], s[22:23]
	v_cmp_gt_i32_e64 s[18:19], 40, v223
	s_and_b64 s[20:21], s[22:23], s[20:21]
	v_cmp_gt_i32_e64 s[16:17], 35, v223
	s_and_b64 s[18:19], s[20:21], s[18:19]
	v_cmp_gt_i32_e64 s[14:15], 34, v223
	s_and_b64 s[16:17], s[18:19], s[16:17]
	v_cmp_gt_i32_e64 s[12:13], 33, v223
	s_and_b64 s[14:15], s[16:17], s[14:15]
	v_cmp_gt_i32_e32 vcc, 32, v223
	s_and_b64 s[12:13], s[14:15], s[12:13]
	s_and_b64 vcc, s[12:13], vcc
	v_cndmask_b32_e64 v127, v127, v205, s[74:75]
	v_cndmask_b32_e64 v126, v126, v205, s[72:73]
	v_cndmask_b32_e64 v125, v125, v205, s[70:71]
	v_cndmask_b32_e64 v124, v124, v205, s[68:69]
	v_cndmask_b32_e64 v123, v123, v205, s[66:67]
	v_cndmask_b32_e64 v122, v122, v205, s[64:65]
	v_cndmask_b32_e64 v121, v121, v205, s[62:63]
	v_cndmask_b32_e64 v120, v120, v205, s[60:61]
	v_cndmask_b32_e64 v119, v119, v205, s[58:59]
	v_cndmask_b32_e64 v118, v118, v205, s[56:57]
	v_cndmask_b32_e64 v117, v117, v205, s[54:55]
	v_cndmask_b32_e64 v116, v116, v205, s[52:53]
	v_cndmask_b32_e64 v115, v115, v205, s[50:51]
	v_cndmask_b32_e64 v114, v114, v205, s[48:49]
	v_cndmask_b32_e64 v113, v113, v205, s[46:47]
	v_cndmask_b32_e64 v111, v111, v205, s[44:45]
	v_cndmask_b32_e64 v110, v110, v205, s[40:41]
	v_cndmask_b32_e64 v109, v109, v205, s[38:39]
	v_cndmask_b32_e64 v108, v108, v205, s[36:37]
	v_cndmask_b32_e64 v107, v107, v205, s[34:35]
	v_cndmask_b32_e64 v106, v106, v205, s[30:31]
	v_cndmask_b32_e64 v105, v105, v205, s[28:29]
	v_cndmask_b32_e64 v104, v104, v205, s[26:27]
	v_cndmask_b32_e64 v103, v103, v205, s[24:25]
	v_cndmask_b32_e64 v102, v102, v205, s[22:23]
	v_cndmask_b32_e64 v101, v101, v205, s[20:21]
	v_cndmask_b32_e64 v100, v100, v205, s[18:19]
	v_cndmask_b32_e64 v99, v99, v205, s[16:17]
	v_cndmask_b32_e64 v98, v98, v205, s[14:15]
	v_cndmask_b32_e64 v97, v97, v205, s[12:13]
	v_cndmask_b32_e32 v96, v96, v205, vcc
	v_readlane_b32 s54, v255, 30
	v_readlane_b32 s55, v255, 31

; __device__ __forceinline__ void partialSM(f32x16& p0, f32x16& p1, float& m_reg, float& mn, float& alpha) {
;     float pmax = p0[0]; for (int r = 1; r < 16; ++r) pmax = fmaxf(pmax, p0[r]); for (int r = 0; r < 16; ++r) pmax = fmaxf(pmax, p1[r]);
;     { auto rr = __builtin_amdgcn_permlane32_swap(__float_as_uint(pmax), __float_as_uint(pmax), false, false);
;       pmax = fmaxf(__uint_as_float(rr[0]), __uint_as_float(rr[1])); }
;     constexpr float C2 = 1.4426950408889634f * SCALE;
;     if (__builtin_expect(__all((pmax - m_reg) * SCALE <= THR), 1)) { mn = m_reg; alpha = 1.f; }
;     else { mn = fmaxf(m_reg, pmax); alpha = __builtin_amdgcn_exp2f((m_reg - mn) * C2); m_reg = mn; }
;     const float mnL = -mn * C2;
;     for (int r = 0; r < 16; ++r) p0[r] = fmaf(p0[r], C2, mnL); for (int r = 0; r < 16; ++r) p1[r] = fmaf(p1[r], C2, mnL);
;     for (int r = 0; r < 16; ++r) p0[r] = __builtin_amdgcn_exp2f(p0[r]);
; }
; template <int VB>
; __device__ __forceinline__ void pv_tile(f32x16* o, int vb0, bf16x8 pa0, bf16x8 pa1, bf16x8 pa2, bf16x8 pa3) {
;     ...
;     PV_D0(0); PV_D0(1); PV_D0(2); PV_D0(3);
.Lhs2_join:
	v_mul_f32_e32 v178, 0xbe0293ee, v176
	v_mfma_f32_32x32x16_bf16 v[48:63], v[68:71], v[242:245], v[48:63]
	ds_read_b64_tr_b16 v[242:243], v209 offset:0x5400
	ds_read_b64_tr_b16 v[244:245], v209 offset:0x5c00
	v_fmamk_f32 v80, v112, 0x3e0293ee, v178
	v_fmamk_f32 v81, v113, 0x3e0293ee, v178
	v_fmamk_f32 v82, v114, 0x3e0293ee, v178
	v_fmamk_f32 v83, v115, 0x3e0293ee, v178
	v_fmamk_f32 v84, v116, 0x3e0293ee, v178
	v_fmamk_f32 v85, v117, 0x3e0293ee, v178
	v_fmamk_f32 v86, v118, 0x3e0293ee, v178
	v_fmamk_f32 v87, v119, 0x3e0293ee, v178
	s_waitcnt lgkmcnt(4)
	v_mfma_f32_32x32x16_bf16 v[48:63], v[72:75], v[246:249], v[48:63]
	ds_read_b64_tr_b16 v[246:247], v209 offset:0x6400
	ds_read_b64_tr_b16 v[248:249], v209 offset:0x6c00
	v_fmamk_f32 v88, v120, 0x3e0293ee, v178
	v_fmamk_f32 v89, v121, 0x3e0293ee, v178
	v_fmamk_f32 v90, v122, 0x3e0293ee, v178
	v_fmamk_f32 v91, v123, 0x3e0293ee, v178
	v_fmamk_f32 v92, v124, 0x3e0293ee, v178
	v_fmamk_f32 v93, v125, 0x3e0293ee, v178
	v_fmamk_f32 v94, v126, 0x3e0293ee, v178
	v_fmamk_f32 v95, v127, 0x3e0293ee, v178
	v_mfma_f32_32x32x16_bf16 v[48:63], v[76:79], v[250:253], v[48:63]
	ds_read_b64_tr_b16 v[250:251], v209 offset:0x7400
	ds_read_b64_tr_b16 v[252:253], v209 offset:0x7c00
	v_fmamk_f32 v126, v96, 0x3e0293ee, v178
	v_fmamk_f32 v127, v97, 0x3e0293ee, v178
	v_fmamk_f32 v112, v110, 0x3e0293ee, v178
	v_fmamk_f32 v113, v111, 0x3e0293ee, v178
	v_fmamk_f32 v114, v108, 0x3e0293ee, v178
	v_fmamk_f32 v115, v109, 0x3e0293ee, v178
	v_fmamk_f32 v116, v106, 0x3e0293ee, v178
	v_fmamk_f32 v117, v107, 0x3e0293ee, v178
	s_waitcnt lgkmcnt(4)
	v_mfma_f32_32x32x16_bf16 v[32:47], v[64:67], v[196:199], v[32:47]
	ds_read_b64_tr_b16 v[196:197], v209 offset:0x4600
	ds_read_b64_tr_b16 v[198:199], v209 offset:0x4e00
	v_fmamk_f32 v118, v104, 0x3e0293ee, v178
	v_fmamk_f32 v119, v105, 0x3e0293ee, v178
	v_fmamk_f32 v120, v102, 0x3e0293ee, v178
	v_fmamk_f32 v121, v103, 0x3e0293ee, v178
	v_fmamk_f32 v122, v100, 0x3e0293ee, v178
	v_fmamk_f32 v123, v101, 0x3e0293ee, v178
	v_fmamk_f32 v124, v98, 0x3e0293ee, v178
	v_fmamk_f32 v125, v99, 0x3e0293ee, v178
	v_mfma_f32_32x32x16_bf16 v[32:47], v[68:71], v[242:245], v[32:47]
	ds_read_b64_tr_b16 v[242:243], v209 offset:0x5600
	ds_read_b64_tr_b16 v[244:245], v209 offset:0x5e00
	v_mov_b32_e32 v96, v179
	v_exp_f32_e32 v237, v80
	v_exp_f32_e32 v239, v81
	v_exp_f32_e32 v235, v82
	v_exp_f32_e32 v238, v83
	s_waitcnt lgkmcnt(4)
	v_mfma_f32_32x32x16_bf16 v[32:47], v[72:75], v[246:249], v[32:47]
	ds_read_b64_tr_b16 v[246:247], v209 offset:0x6600
	ds_read_b64_tr_b16 v[248:249], v209 offset:0x6e00
	v_exp_f32_e32 v234, v84
	v_exp_f32_e32 v236, v85
	v_exp_f32_e32 v232, v86
	v_exp_f32_e32 v233, v87
	v_mfma_f32_32x32x16_bf16 v[32:47], v[76:79], v[250:253], v[32:47]
	ds_read_b64_tr_b16 v[250:251], v209 offset:0x7600
	ds_read_b64_tr_b16 v[252:253], v209 offset:0x7e00
	v_exp_f32_e32 v228, v88
	v_exp_f32_e32 v231, v89
	v_exp_f32_e32 v179, v90
	v_exp_f32_e32 v229, v91
	s_waitcnt lgkmcnt(4)
	v_mfma_f32_32x32x16_bf16 v[16:31], v[64:67], v[196:199], v[16:31]
	v_exp_f32_e32 v177, v92
	v_exp_f32_e32 v230, v93
	v_exp_f32_e32 v178, v94
	v_exp_f32_e32 v227, v95
	v_mfma_f32_32x32x16_bf16 v[16:31], v[68:71], v[242:245], v[16:31]
	s_waitcnt lgkmcnt(0)
	v_mfma_f32_32x32x16_bf16 v[16:31], v[72:75], v[246:249], v[16:31]
	v_mfma_f32_32x32x16_bf16 v[16:31], v[76:79], v[250:253], v[16:31]
	s_andn2_b64 vcc, exec, s[42:43]
	s_cbranch_vccnz .Lhs2_bar1
	s_waitcnt vmcnt(0)
	s_and_b64 vcc, exec, s[10:11]
	ds_write_b128 v208, v[164:167] offset:49152
	ds_write_b128 v208, v[172:175] offset:57344
	s_cbranch_vccnz .Lhs2_bar1
	s_mov_b32 s10, 0x667f3bcd
	v_add_f64 v[64:65], s[94:95], -v[188:189]
	s_mov_b32 s11, 0x4026a09e
	v_mul_f64 v[64:65], v[64:65], s[10:11]
	v_cvt_f32_f64_e32 v64, v[64:65]
	ds_write_b32 v221, v64 offset:256
